# phase-2 indexer work table regrouped so each batch's items run on one XCD (L2 locality), balanced
# speedup vs baseline: 1.0137x; 1.0010x over previous
_ZL7idx_tab:
	.short	32
	.short	214
	.short	148
	.short	65535
	.short	65535
	.short	160
	.short	343
	.short	337
	.short	450
	.short	65535
	.short	288
	.short	597
	.short	661
	.short	65535
	.short	65535
	.short	416
	.short	851
	.short	915
	.short	65535
	.short	65535
	.short	1053
	.short	1051
	.short	1230
	.short	65535
	.short	65535
	.short	672
	.short	1429
	.short	1364
	.short	65535
	.short	65535
	.short	800
	.short	1682
	.short	1746
	.short	65535
	.short	65535
	.short	928
	.short	1875
	.short	1938
	.short	65535
	.short	65535
	.short	155
	.short	215
	.short	150
	.short	65535
	.short	65535
	.short	224
	.short	407
	.short	274
	.short	65535
	.short	65535
	.short	352
	.short	726
	.short	531
	.short	65535
	.short	65535
	.short	480
	.short	981
	.short	977
	.short	65535
	.short	65535
	.short	608
	.short	1239
	.short	1172
	.short	65535
	.short	65535
	.short	736
	.short	1430
	.short	1428
	.short	65535
	.short	65535
	.short	864
	.short	1687
	.short	1619
	.short	65535
	.short	65535
	.short	992
	.short	1943
	.short	1940
	.short	65535
	.short	65535
	.short	31
	.short	22
	.short	212
	.short	130
	.short	65535
	.short	287
	.short	278
	.short	404
	.short	386
	.short	65535
	.short	603
	.short	727
	.short	662
	.short	642
	.short	65535
	.short	799
	.short	850
	.short	786
	.short	898
	.short	65535
	.short	1055
	.short	1175
	.short	1042
	.short	1154
	.short	65535
	.short	1311
	.short	1427
	.short	1490
	.short	1410
	.short	65535
	.short	1694
	.short	1563
	.short	1551
	.short	65535
	.short	65535
	.short	1823
	.short	1815
	.short	1937
	.short	1922
	.short	65535
	.short	95
	.short	19
	.short	211
	.short	194
	.short	65535
	.short	351
	.short	470
	.short	466
	.short	65535
	.short	65535
	.short	607
	.short	533
	.short	722
	.short	706
	.short	65535
	.short	863
	.short	983
	.short	980
	.short	962
	.short	65535
	.short	1119
	.short	1174
	.short	1237
	.short	1218
	.short	65535
	.short	1375
	.short	1365
	.short	1362
	.short	1474
	.short	65535
	.short	1631
	.short	1747
	.short	1555
	.short	1730
	.short	65535
	.short	1887
	.short	1819
	.short	1871
	.short	65535
	.short	65535
	.short	159
	.short	28
	.short	76
	.short	131
	.short	65535
	.short	415
	.short	277
	.short	276
	.short	387
	.short	65535
	.short	671
	.short	598
	.short	659
	.short	643
	.short	65535
	.short	927
	.short	913
	.short	784
	.short	899
	.short	65535
	.short	1183
	.short	1109
	.short	1236
	.short	1155
	.short	65535
	.short	1439
	.short	1301
	.short	1299
	.short	1411
	.short	65535
	.short	1630
	.short	1686
	.short	1749
	.short	1667
	.short	65535
	.short	1951
	.short	1942
	.short	2005
	.short	1923
	.short	65535
	.short	223
	.short	82
	.short	146
	.short	195
	.short	65535
	.short	479
	.short	340
	.short	403
	.short	451
	.short	65535
	.short	731
	.short	663
	.short	534
	.short	65535
	.short	65535
	.short	796
	.short	987
	.short	975
	.short	963
	.short	65535
	.short	1247
	.short	1233
	.short	1169
	.short	1219
	.short	65535
	.short	1308
	.short	1303
	.short	1367
	.short	1475
	.short	65535
	.short	1566
	.short	1559
	.short	1684
	.short	1731
	.short	1601
	.short	2015
	.short	2011
	.short	1999
	.short	65535
	.short	65535
	.short	30
	.short	149
	.short	21
	.short	2
	.short	128
	.short	286
	.short	469
	.short	275
	.short	258
	.short	384
	.short	542
	.short	723
	.short	530
	.short	514
	.short	640
	.short	798
	.short	982
	.short	916
	.short	770
	.short	896
	.short	1054
	.short	1046
	.short	1107
	.short	1026
	.short	1152
	.short	1310
	.short	1366
	.short	1493
	.short	1282
	.short	1408
	.short	1759
	.short	1622
	.short	1620
	.short	1538
	.short	1664
	.short	1822
	.short	1879
	.short	1812
	.short	1794
	.short	1920
	.short	94
	.short	85
	.short	20
	.short	66
	.short	192
	.short	350
	.short	284
	.short	334
	.short	448
	.short	65535
	.short	606
	.short	599
	.short	595
	.short	578
	.short	704
	.short	862
	.short	853
	.short	787
	.short	834
	.short	960
	.short	544
	.short	1111
	.short	1106
	.short	1090
	.short	1216
	.short	1374
	.short	1302
	.short	1494
	.short	1346
	.short	1472
	.short	1695
	.short	1685
	.short	1556
	.short	1602
	.short	1728
	.short	1947
	.short	2007
	.short	1813
	.short	1858
	.short	1984
	.short	158
	.short	23
	.short	83
	.short	3
	.short	129
	.short	414
	.short	402
	.short	338
	.short	259
	.short	385
	.short	670
	.short	596
	.short	658
	.short	515
	.short	641
	.short	926
	.short	789
	.short	852
	.short	771
	.short	897
	.short	1182
	.short	1045
	.short	1170
	.short	1027
	.short	1153
	.short	1438
	.short	1372
	.short	1422
	.short	1283
	.short	1409
	.short	1567
	.short	1627
	.short	1546
	.short	1665
	.short	65535
	.short	1950
	.short	2006
	.short	2003
	.short	1795
	.short	1921
	.short	222
	.short	210
	.short	81
	.short	67
	.short	193
	.short	478
	.short	468
	.short	339
	.short	323
	.short	449
	.short	734
	.short	724
	.short	660
	.short	579
	.short	705
	.short	797
	.short	988
	.short	974
	.short	835
	.short	961
	.short	1246
	.short	1047
	.short	1234
	.short	1091
	.short	1217
	.short	1502
	.short	1363
	.short	1426
	.short	1347
	.short	1473
	.short	1758
	.short	1750
	.short	1621
	.short	1603
	.short	1729
	.short	2014
	.short	1814
	.short	1877
	.short	1859
	.short	1985
	.short	29
	.short	78
	.short	14
	.short	197
	.short	65535
	.short	285
	.short	270
	.short	269
	.short	389
	.short	65535
	.short	543
	.short	525
	.short	651
	.short	519
	.short	65535
	.short	990
	.short	973
	.short	781
	.short	900
	.short	65535
	.short	1244
	.short	1039
	.short	1102
	.short	1156
	.short	65535
	.short	1307
	.short	1359
	.short	1293
	.short	1415
	.short	65535
	.short	1565
	.short	1549
	.short	1739
	.short	1542
	.short	65535
	.short	1821
	.short	1997
	.short	1805
	.short	1799
	.short	65535
	.short	93
	.short	142
	.short	13
	.short	70
	.short	65535
	.short	349
	.short	463
	.short	395
	.short	327
	.short	65535
	.short	541
	.short	590
	.short	589
	.short	517
	.short	65535
	.short	861
	.short	782
	.short	845
	.short	773
	.short	65535
	.short	1243
	.short	1038
	.short	1101
	.short	1095
	.short	65535
	.short	1373
	.short	1294
	.short	1357
	.short	1350
	.short	65535
	.short	1629
	.short	1613
	.short	1740
	.short	1605
	.short	1600
	.short	1885
	.short	1806
	.short	1869
	.short	1925
	.short	65535
	.short	157
	.short	147
	.short	18
	.short	0
	.short	1
	.short	413
	.short	406
	.short	467
	.short	256
	.short	257
	.short	669
	.short	535
	.short	532
	.short	512
	.short	513
	.short	925
	.short	919
	.short	788
	.short	768
	.short	769
	.short	1181
	.short	1242
	.short	1167
	.short	1024
	.short	1025
	.short	1437
	.short	1309
	.short	1421
	.short	1280
	.short	1281
	.short	1693
	.short	1692
	.short	1677
	.short	1536
	.short	1537
	.short	1949
	.short	1820
	.short	1933
	.short	1792
	.short	1793
	.short	221
	.short	151
	.short	84
	.short	64
	.short	65
	.short	477
	.short	342
	.short	341
	.short	320
	.short	321
	.short	733
	.short	604
	.short	717
	.short	576
	.short	577
	.short	989
	.short	918
	.short	917
	.short	832
	.short	833
	.short	1245
	.short	1238
	.short	1108
	.short	1088
	.short	1089
	.short	1501
	.short	1306
	.short	1485
	.short	1344
	.short	1345
	.short	1757
	.short	1623
	.short	1748
	.short	65535
	.short	65535
	.short	2013
	.short	2004
	.short	1811
	.short	1856
	.short	1857
	.short	26
	.short	10
	.short	202
	.short	200
	.short	65535
	.short	474
	.short	400
	.short	393
	.short	388
	.short	65535
	.short	540
	.short	653
	.short	524
	.short	645
	.short	65535
	.short	986
	.short	843
	.short	778
	.short	840
	.short	65535
	.short	1052
	.short	1164
	.short	1036
	.short	1030
	.short	65535
	.short	1503
	.short	1420
	.short	1292
	.short	1479
	.short	65535
	.short	1626
	.short	1744
	.short	1736
	.short	1668
	.short	65535
	.short	2010
	.short	2000
	.short	1929
	.short	1988
	.short	65535
	.short	92
	.short	205
	.short	77
	.short	135
	.short	65535
	.short	411
	.short	399
	.short	398
	.short	452
	.short	65535
	.short	667
	.short	655
	.short	588
	.short	646
	.short	65535
	.short	860
	.short	910
	.short	909
	.short	966
	.short	65535
	.short	1171
	.short	1040
	.short	1227
	.short	1098
	.short	65535
	.short	1369
	.short	1361
	.short	1289
	.short	1412
	.short	65535
	.short	1754
	.short	1550
	.short	1741
	.short	1671
	.short	1539
	.short	1884
	.short	1998
	.short	1868
	.short	1926
	.short	65535
	.short	156
	.short	207
	.short	140
	.short	69
	.short	65535
	.short	282
	.short	273
	.short	264
	.short	260
	.short	65535
	.short	668
	.short	718
	.short	652
	.short	583
	.short	65535
	.short	924
	.short	783
	.short	908
	.short	775
	.short	65535
	.short	1180
	.short	1229
	.short	1099
	.short	1028
	.short	65535
	.short	1371
	.short	1488
	.short	1352
	.short	1284
	.short	65535
	.short	1755
	.short	1742
	.short	1676
	.short	1543
	.short	65535
	.short	1881
	.short	1810
	.short	1928
	.short	1796
	.short	65535
	.short	220
	.short	79
	.short	11
	.short	199
	.short	65535
	.short	476
	.short	462
	.short	460
	.short	262
	.short	65535
	.short	666
	.short	529
	.short	584
	.short	708
	.short	65535
	.short	856
	.short	914
	.short	969
	.short	836
	.short	65535
	.short	1112
	.short	1104
	.short	1035
	.short	1092
	.short	65535
	.short	1500
	.short	1492
	.short	1285
	.short	1349
	.short	65535
	.short	1624
	.short	1617
	.short	1544
	.short	1669
	.short	65535
	.short	2012
	.short	1996
	.short	1802
	.short	1861
	.short	65535
	.short	154
	.short	138
	.short	137
	.short	201
	.short	65535
	.short	283
	.short	333
	.short	396
	.short	390
	.short	65535
	.short	732
	.short	591
	.short	523
	.short	711
	.short	65535
	.short	795
	.short	847
	.short	846
	.short	902
	.short	65535
	.short	1116
	.short	1166
	.short	1228
	.short	1158
	.short	65535
	.short	1432
	.short	1296
	.short	1417
	.short	1414
	.short	65535
	.short	1752
	.short	1553
	.short	1608
	.short	1541
	.short	65535
	.short	1941
	.short	1870
	.short	1803
	.short	1867
	.short	65535
	.short	217
	.short	144
	.short	9
	.short	132
	.short	65535
	.short	473
	.short	459
	.short	266
	.short	457
	.short	65535
	.short	605
	.short	654
	.short	716
	.short	710
	.short	707
	.short	793
	.short	972
	.short	970
	.short	776
	.short	65535
	.short	1241
	.short	1165
	.short	1096
	.short	1160
	.short	65535
	.short	1499
	.short	1486
	.short	1484
	.short	1351
	.short	65535
	.short	1554
	.short	1745
	.short	1611
	.short	1738
	.short	65535
	.short	1948
	.short	1876
	.short	1927
	.short	1990
	.short	1987
	.short	96
	.short	141
	.short	204
	.short	5
	.short	65535
	.short	348
	.short	405
	.short	263
	.short	261
	.short	65535
	.short	602
	.short	656
	.short	585
	.short	580
	.short	65535
	.short	984
	.short	976
	.short	907
	.short	964
	.short	65535
	.short	1179
	.short	1231
	.short	1037
	.short	1157
	.short	65535
	.short	1498
	.short	1290
	.short	1418
	.short	1353
	.short	65535
	.short	1564
	.short	1743
	.short	1548
	.short	1670
	.short	65535
	.short	1817
	.short	1808
	.short	1866
	.short	1924
	.short	65535
	.short	90
	.short	208
	.short	73
	.short	4
	.short	65535
	.short	475
	.short	271
	.short	332
	.short	326
	.short	322
	.short	601
	.short	592
	.short	522
	.short	516
	.short	65535
	.short	858
	.short	848
	.short	904
	.short	837
	.short	65535
	.short	1118
	.short	1103
	.short	1100
	.short	1093
	.short	65535
	.short	1370
	.short	1297
	.short	1288
	.short	1348
	.short	65535
	.short	1557
	.short	1679
	.short	1615
	.short	1612
	.short	1666
	.short	1882
	.short	1807
	.short	1995
	.short	1863
	.short	65535
	.short	89
	.short	80
	.short	72
	.short	198
	.short	65535
	.short	346
	.short	335
	.short	461
	.short	391
	.short	65535
	.short	538
	.short	719
	.short	715
	.short	647
	.short	65535
	.short	794
	.short	790
	.short	903
	.short	901
	.short	65535
	.short	1049
	.short	1163
	.short	1226
	.short	1225
	.short	65535
	.short	1434
	.short	1489
	.short	1480
	.short	1476
	.short	65535
	.short	1756
	.short	1558
	.short	1734
	.short	1733
	.short	65535
	.short	1818
	.short	1936
	.short	1864
	.short	1989
	.short	65535
	.short	216
	.short	145
	.short	74
	.short	68
	.short	65535
	.short	412
	.short	397
	.short	268
	.short	455
	.short	65535
	.short	539
	.short	526
	.short	586
	.short	582
	.short	65535
	.short	859
	.short	854
	.short	967
	.short	965
	.short	65535
	.short	1117
	.short	1110
	.short	1222
	.short	1221
	.short	65535
	.short	1368
	.short	1425
	.short	1481
	.short	1477
	.short	65535
	.short	1691
	.short	1614
	.short	1547
	.short	1735
	.short	65535
	.short	1878
	.short	1939
	.short	1932
	.short	1991
	.short	65535
	.short	27
	.short	213
	.short	6
	.short	133
	.short	65535
	.short	409
	.short	336
	.short	394
	.short	324
	.short	65535
	.short	735
	.short	527
	.short	650
	.short	518
	.short	65535
	.short	922
	.short	855
	.short	839
	.short	774
	.short	65535
	.short	1178
	.short	1168
	.short	1032
	.short	1029
	.short	65535
	.short	1436
	.short	1487
	.short	1419
	.short	1286
	.short	65535
	.short	1560
	.short	1681
	.short	1545
	.short	1604
	.short	65535
	.short	1946
	.short	1935
	.short	1930
	.short	1798
	.short	65535
	.short	91
	.short	206
	.short	12
	.short	7
	.short	65535
	.short	281
	.short	272
	.short	265
	.short	325
	.short	65535
	.short	730
	.short	721
	.short	648
	.short	644
	.short	65535
	.short	923
	.short	911
	.short	780
	.short	838
	.short	65535
	.short	1115
	.short	1044
	.short	1159
	.short	1094
	.short	65535
	.short	1435
	.short	1358
	.short	1482
	.short	1478
	.short	65535
	.short	1689
	.short	1552
	.short	1737
	.short	1732
	.short	65535
	.short	1886
	.short	1934
	.short	1804
	.short	1862
	.short	65535
	.short	25
	.short	203
	.short	139
	.short	136
	.short	65535
	.short	279
	.short	465
	.short	456
	.short	392
	.short	65535
	.short	537
	.short	587
	.short	714
	.short	521
	.short	65535
	.short	857
	.short	779
	.short	842
	.short	777
	.short	65535
	.short	1235
	.short	1043
	.short	1033
	.short	1161
	.short	65535
	.short	1300
	.short	1295
	.short	1356
	.short	1291
	.short	65535
	.short	1683
	.short	1618
	.short	1674
	.short	1609
	.short	65535
	.short	2002
	.short	1874
	.short	1994
	.short	1801
	.short	65535
	.short	87
	.short	15
	.short	143
	.short	75
	.short	65535
	.short	345
	.short	267
	.short	458
	.short	329
	.short	65535
	.short	725
	.short	594
	.short	713
	.short	712
	.short	65535
	.short	979
	.short	849
	.short	844
	.short	968
	.short	65535
	.short	1113
	.short	1162
	.short	1034
	.short	1097
	.short	65535
	.short	1495
	.short	1423
	.short	1355
	.short	1483
	.short	65535
	.short	1625
	.short	1675
	.short	1610
	.short	1672
	.short	65535
	.short	1883
	.short	1931
	.short	1865
	.short	1992
	.short	65535
	.short	218
	.short	17
	.short	8
	.short	196
	.short	65535
	.short	410
	.short	331
	.short	330
	.short	328
	.short	65535
	.short	665
	.short	720
	.short	649
	.short	709
	.short	65535
	.short	921
	.short	912
	.short	905
	.short	772
	.short	65535
	.short	1114
	.short	1173
	.short	1223
	.short	1031
	.short	65535
	.short	1431
	.short	1491
	.short	1354
	.short	1287
	.short	65535
	.short	1561
	.short	1680
	.short	1673
	.short	1540
	.short	65535
	.short	1945
	.short	1872
	.short	1800
	.short	1797
	.short	1986
	.short	219
	.short	86
	.short	71
	.short	134
	.short	65535
	.short	347
	.short	471
	.short	454
	.short	453
	.short	65535
	.short	729
	.short	528
	.short	520
	.short	581
	.short	65535
	.short	985
	.short	971
	.short	906
	.short	841
	.short	65535
	.short	1050
	.short	1041
	.short	1224
	.short	1220
	.short	65535
	.short	1497
	.short	1360
	.short	1416
	.short	1413
	.short	65535
	.short	1690
	.short	1751
	.short	1607
	.short	1606
	.short	65535
	.short	2009
	.short	1809
	.short	1993
	.short	1860
	.short	65535
	.short	24
	.short	152
	.short	209
	.short	65535
	.short	65535
	.short	280
	.short	408
	.short	464
	.short	65535
	.short	65535
	.short	536
	.short	664
	.short	657
	.short	65535
	.short	65535
	.short	792
	.short	920
	.short	785
	.short	65535
	.short	65535
	.short	1240
	.short	1176
	.short	1105
	.short	65535
	.short	65535
	.short	1305
	.short	1433
	.short	1424
	.short	65535
	.short	65535
	.short	1753
	.short	1688
	.short	1616
	.short	65535
	.short	65535
	.short	1816
	.short	1944
	.short	2001
	.short	65535
	.short	65535
	.short	153
	.short	88
	.short	16
	.short	65535
	.short	65535
	.short	344
	.short	472
	.short	401
	.short	65535
	.short	65535
	.short	600
	.short	728
	.short	593
	.short	65535
	.short	65535
	.short	991
	.short	791
	.short	978
	.short	65535
	.short	65535
	.short	1177
	.short	1048
	.short	1232
	.short	65535
	.short	65535
	.short	1304
	.short	1496
	.short	1298
	.short	65535
	.short	65535
	.short	1628
	.short	1562
	.short	1678
	.short	65535
	.short	65535
	.short	1880
	.short	2008
	.short	1873
	.short	65535
	.short	65535
	.size	_ZL7idx_tab, 2560

	.type	__hip_cuid_794236f6d9ab0dff,@object
